# GEMM epilogues: rope cos/sin loads 3-deep rolling prefetch (was 8 serialized L2 round trips per tile); out-proj gate loads hoisted to unit start
# speedup vs baseline: 1.0136x; 1.0047x over previous
;     __host__ __device__ bool next(int i, Unit& u) const {
;         const long L = (long)i * G + c; if (L >= nwg) return false;
;         int wgid = (int)L; { const int q = nwg / NXCD, r = nwg % NXCD, xcd = wgid % NXCD, off = wgid / NXCD; wgid = (xcd < r ? xcd * (q + 1) : r * (q + 1) + (xcd - r) * q) + off; }
;         const int nig = WGM * nN, gid = wgid / nig, fm = gid * WGM, gsz = (nM - fm) < WGM ? (nM - fm) : WGM;
;         u.pm = fm + ((wgid % nig) % gsz); u.pn = (wgid % nig) / gsz; return true;
;     __device__ __forceinline__ void operator()(const f32x4 (&acc)[2][2][4][2], const Unit& u, int wr, int wc, int fr, int fq) const {
;     ...
;         const float* gp = gate + (size_t)(u.pm >> 4) * 6144 + col0;
;         f32x4 g[2][2];
; #pragma unroll
;         for (int bj = 0; bj < 2; ++bj)
; #pragma unroll
;             for (int n = 0; n < 2; ++n) g[bj][n] = *(const f32x4*)(gp + bj * 128 + n * 4);
.LBB0_88:
	s_ashr_i32 s2, s59, 4
	s_mul_hi_i32 s3, s2, 0x6000
	s_mulk_i32 s2, 0x6000
	v_lshl_or_b32 v244, s60, 8, v164
	s_add_u32 s2, s54, s2
	s_addc_u32 s3, s55, s3
	v_ashrrev_i32_e32 v245, 31, v244
	v_lshl_add_u64 v[244:245], v[244:245], 2, s[2:3]
	global_load_dwordx4 v[228:231], v[244:245], off
	global_load_dwordx4 v[232:235], v[244:245], off offset:16
	global_load_dwordx4 v[236:239], v[244:245], off offset:512
	global_load_dwordx4 v[240:243], v[244:245], off offset:528
	s_add_i32 s58, s58, 1
	s_mul_i32 s2, s58, s95
	s_mul_hi_u32 s3, s58, s62
	s_add_i32 s3, s3, s2
	s_mul_i32 s2, s58, s62
	s_add_u32 s46, s2, s77
	s_addc_u32 s47, s3, s90
	v_mov_b64_e32 v[2:3], 0x200
	v_cmp_lt_i64_e64 s[40:41], s[46:47], v[2:3]
	v_mov_b64_e32 v[2:3], 0x1ff
	v_cmp_gt_i64_e32 vcc, s[46:47], v[2:3]
	s_cbranch_vccnz .LBB0_94
	s_ashr_i32 s2, s46, 31
	s_lshr_b32 s2, s2, 29
	s_add_i32 s2, s46, s2
	s_and_b32 s3, s2, -8
	s_sub_i32 s3, s46, s3
	s_cmp_gt_i32 s3, -1
	s_mov_b64 s[42:43], -1
	s_cbranch_scc0 .LBB0_91
	s_lshl_b32 s20, s3, 6
	s_mov_b64 s[42:43], 0

; __device__ __forceinline__ void st8(bf16_t* p, const float (&v)[8]) { u32x4 w; w.x = pk2(v[0], v[1]); w.y = pk2(v[2], v[3]); w.z = pk2(v[4], v[5]); w.w = pk2(v[6], v[7]); *(u32x4*)p = w; }
;     __device__ __forceinline__ void operator()(const f32x4 (&acc)[2][2][4][2], const Unit& u, int wr, int wc, int fr, int fq) const {
;     ...
; #pragma unroll
;         for (int ai = 0; ai < 2; ++ai)
; #pragma unroll
;             for (int m = 0; m < 4; ++m) { bf16_t* rp = dl + (size_t)(row0 + ai * 128 + m * 16) * DM + col0;
; #pragma unroll
;                 for (int bj = 0; bj < 2; ++bj) { float o[8];
; #pragma unroll
;                     for (int j = 0; j < 4; ++j) { o[j] = g[bj][0][j] * acc[ai][bj][m][0][j]; o[4 + j] = g[bj][1][j] * acc[ai][bj][m][1][j]; }
;                     st8(rp + bj * 128, o); } }
.LBB0_98:
	s_ashr_i32 s2, s59, 4
	s_mul_hi_i32 s3, s2, 0x6000
	s_mulk_i32 s2, 0x6000
	v_lshl_or_b32 v156, s60, 8, v164
	s_add_u32 s2, s54, s2
	s_addc_u32 s3, s55, s3
	v_ashrrev_i32_e32 v157, 31, v156
	v_lshl_add_u64 v[118:119], v[156:157], 2, s[2:3]
	v_mov_b32_e32 v122, v228
	v_mov_b32_e32 v123, v229
	v_mov_b32_e32 v124, v230
	v_mov_b32_e32 v125, v231
	v_mov_b32_e32 v126, v232
	v_mov_b32_e32 v127, v233
	v_mov_b32_e32 v128, v234
	v_mov_b32_e32 v129, v235
	v_mov_b32_e32 v114, v236
	v_mov_b32_e32 v115, v237
	v_mov_b32_e32 v116, v238
	v_mov_b32_e32 v117, v239
	v_mov_b32_e32 v118, v240
	v_mov_b32_e32 v119, v241
	v_mov_b32_e32 v120, v242
	v_mov_b32_e32 v121, v243
	v_lshl_add_u32 v160, s59, 8, v162
	v_ashrrev_i32_e32 v161, 31, v160
	v_lshlrev_b64 v[158:159], 12, v[160:161]
	v_lshl_add_u64 v[166:167], s[16:17], 0, v[158:159]
	v_lshlrev_b64 v[158:159], 1, v[156:157]
	v_lshl_add_u64 v[156:157], v[166:167], 0, v[158:159]
	s_mov_b64 s[2:3], 0x80000
	s_mov_b64 s[24:25], -1
	s_waitcnt lgkmcnt(0)
	v_mul_f32_e32 v142, v142, v122
	v_mul_f32_e32 v161, v138, v126
	v_mul_f32_e32 v138, v143, v123
	v_mul_f32_e32 v143, v139, v127
	v_mul_f32_e32 v139, v144, v124
	v_mul_f32_e32 v144, v140, v128
	v_mul_f32_e32 v140, v145, v125
	v_mul_f32_e32 v141, v141, v129
	v_cvt_pk_bf16_f32 v138, v142, v138
	v_cvt_pk_bf16_f32 v139, v139, v140
	v_cvt_pk_bf16_f32 v140, v161, v143
	v_cvt_pk_bf16_f32 v141, v144, v141
	global_store_dwordx4 v[156:157], v[138:141], off
	v_mul_f32_e32 v134, v134, v114
	v_mul_f32_e32 v133, v133, v121
	v_mul_f32_e32 v138, v130, v118
	v_mul_f32_e32 v130, v135, v115
	v_mul_f32_e32 v135, v131, v119
	v_mul_f32_e32 v131, v136, v116
	v_mul_f32_e32 v136, v132, v120
	v_mul_f32_e32 v132, v137, v117
	v_cvt_pk_bf16_f32 v130, v134, v130
	v_cvt_pk_bf16_f32 v131, v131, v132
	v_cvt_pk_bf16_f32 v132, v138, v135
	v_cvt_pk_bf16_f32 v133, v136, v133
	global_store_dwordx4 v[156:157], v[130:133], off offset:256
	v_mul_f32_e32 v110, v110, v122
	v_mul_f32_e32 v109, v109, v129
	v_or_b32_e32 v130, 16, v160
	v_ashrrev_i32_e32 v131, 31, v130
	v_lshlrev_b64 v[130:131], 12, v[130:131]
	v_lshl_add_u64 v[130:131], s[16:17], 0, v[130:131]
	v_mul_f32_e32 v132, v106, v126
	v_mul_f32_e32 v106, v111, v123
	v_lshl_add_u64 v[130:131], v[130:131], 0, v[158:159]
	v_mul_f32_e32 v111, v107, v127
	v_mul_f32_e32 v107, v112, v124
	v_mul_f32_e32 v112, v108, v128
	v_mul_f32_e32 v108, v113, v125
	v_cvt_pk_bf16_f32 v106, v110, v106
	v_cvt_pk_bf16_f32 v107, v107, v108
	v_cvt_pk_bf16_f32 v108, v132, v111
	v_cvt_pk_bf16_f32 v109, v112, v109
	global_store_dwordx4 v[130:131], v[106:109], off
	v_mul_f32_e32 v102, v102, v114
	v_mul_f32_e32 v101, v101, v121
	v_mul_f32_e32 v106, v98, v118
	v_mul_f32_e32 v98, v103, v115
	v_mul_f32_e32 v103, v99, v119
	v_mul_f32_e32 v99, v104, v116
	v_mul_f32_e32 v104, v100, v120
	v_mul_f32_e32 v100, v105, v117
	v_cvt_pk_bf16_f32 v98, v102, v98
	v_cvt_pk_bf16_f32 v99, v99, v100
	v_cvt_pk_bf16_f32 v100, v106, v103
	v_cvt_pk_bf16_f32 v101, v104, v101
	global_store_dwordx4 v[130:131], v[98:101], off offset:256
	v_mul_f32_e32 v94, v94, v122
	v_mul_f32_e32 v93, v93, v129
	v_or_b32_e32 v98, 32, v160
	v_ashrrev_i32_e32 v99, 31, v98
	v_lshlrev_b64 v[98:99], 12, v[98:99]
	v_lshl_add_u64 v[98:99], s[16:17], 0, v[98:99]
	v_mul_f32_e32 v100, v90, v126
	v_mul_f32_e32 v90, v95, v123
	v_lshl_add_u64 v[98:99], v[98:99], 0, v[158:159]
	v_mul_f32_e32 v95, v91, v127
	v_mul_f32_e32 v91, v96, v124
	v_mul_f32_e32 v96, v92, v128
	v_mul_f32_e32 v92, v97, v125
	v_cvt_pk_bf16_f32 v90, v94, v90
	v_cvt_pk_bf16_f32 v91, v91, v92
	v_cvt_pk_bf16_f32 v92, v100, v95
	v_cvt_pk_bf16_f32 v93, v96, v93
	global_store_dwordx4 v[98:99], v[90:93], off
	v_mul_f32_e32 v82, v82, v114
	v_mul_f32_e32 v77, v77, v121
	v_mul_f32_e32 v90, v74, v118
	v_mul_f32_e32 v74, v83, v115
	v_mul_f32_e32 v83, v75, v119
	v_mul_f32_e32 v75, v84, v116
	v_mul_f32_e32 v84, v76, v120
	v_mul_f32_e32 v76, v85, v117
	v_cvt_pk_bf16_f32 v74, v82, v74
	v_cvt_pk_bf16_f32 v75, v75, v76
	v_cvt_pk_bf16_f32 v76, v90, v83
	v_cvt_pk_bf16_f32 v77, v84, v77
	global_store_dwordx4 v[98:99], v[74:77], off offset:256
	v_mul_f32_e32 v81, v81, v129
	v_mul_f32_e32 v70, v70, v114
	v_or_b32_e32 v74, 48, v160
	v_ashrrev_i32_e32 v75, 31, v74
	v_lshlrev_b64 v[74:75], 12, v[74:75]
	v_lshl_add_u64 v[74:75], s[16:17], 0, v[74:75]
	v_lshl_add_u64 v[82:83], v[74:75], 0, v[158:159]
	v_mul_f32_e32 v74, v86, v122
	v_mul_f32_e32 v76, v78, v126
	v_mul_f32_e32 v75, v87, v123
	v_mul_f32_e32 v77, v79, v127
	v_cvt_pk_bf16_f32 v74, v74, v75
	v_mul_f32_e32 v78, v88, v124
	v_mul_f32_e32 v79, v80, v128
	v_mul_f32_e32 v80, v89, v125
	v_cvt_pk_bf16_f32 v75, v78, v80
	v_cvt_pk_bf16_f32 v76, v76, v77
	v_cvt_pk_bf16_f32 v77, v79, v81
; #define PG8_BAR __builtin_amdgcn_s_barrier()
; __device__ __forceinline__ void st8(bf16_t* p, const float (&v)[8]) { u32x4 w; w.x = pk2(v[0], v[1]); w.y = pk2(v[2], v[3]); w.z = pk2(v[4], v[5]); w.w = pk2(v[6], v[7]); *(u32x4*)p = w; }
; template <class Epi, class Sched, bool ALIGN_EPI = false, bool SP2 = false>
; __device__ __forceinline__ void gemm_phase(PG8_LAS unsigned char* lds, const Gemm g, const Sched& S, const Epi& E) {
;     ...
;         if (!has_next) break;
; #pragma unroll
;         for (int a = 0; a < 2; ++a)
; #pragma unroll
;             for (int b = 0; b < 2; ++b)
; #pragma unroll
;                 for (int m = 0; m < 4; ++m)
; #pragma unroll
;                     for (int n = 0; n < 2; ++n) acc[a][b][m][n] = (f32x4){0.f, 0.f, 0.f, 0.f};
;         cur = nxt; cA = nA; cB = nB; ++ui;
;         if constexpr (ALIGN_EPI) { if (wr == 1) PG8_BAR; }
;     }
;     __device__ __forceinline__ void operator()(const f32x4 (&acc)[2][2][4][2], const Unit& u, int wr, int wc, int fr, int fq) const {
;     ...
; #pragma unroll
;         for (int ai = 0; ai < 2; ++ai)
; #pragma unroll
;             for (int m = 0; m < 4; ++m) { bf16_t* rp = dl + (size_t)(row0 + ai * 128 + m * 16) * DM + col0;
; #pragma unroll
;                 for (int bj = 0; bj < 2; ++bj) { float o[8];
; #pragma unroll
;                     for (int j = 0; j < 4; ++j) { o[j] = g[bj][0][j] * acc[ai][bj][m][0][j]; o[4 + j] = g[bj][1][j] * acc[ai][bj][m][1][j]; }
;                     st8(rp + bj * 128, o); } }
	global_store_dwordx4 v[82:83], v[74:77], off
	v_mul_f32_e32 v69, v69, v121
	v_mul_f32_e32 v62, v62, v122
	v_mul_f32_e32 v74, v66, v118
	v_mul_f32_e32 v66, v71, v115
	v_mul_f32_e32 v71, v67, v119
	v_mul_f32_e32 v67, v72, v116
	v_mul_f32_e32 v72, v68, v120
	v_mul_f32_e32 v68, v73, v117
	v_cvt_pk_bf16_f32 v66, v70, v66
	v_cvt_pk_bf16_f32 v67, v67, v68
	v_cvt_pk_bf16_f32 v68, v74, v71
	v_cvt_pk_bf16_f32 v69, v72, v69
	global_store_dwordx4 v[82:83], v[66:69], off offset:256
	v_mul_f32_e32 v61, v61, v129
	v_mul_f32_e32 v46, v46, v114
	v_lshl_add_u64 v[66:67], v[156:157], 0, s[2:3]
	v_mul_f32_e32 v68, v58, v126
	v_mul_f32_e32 v58, v63, v123
	s_mov_b32 s2, 0x80000
	v_mul_f32_e32 v63, v59, v127
	v_mul_f32_e32 v59, v64, v124
	v_mul_f32_e32 v64, v60, v128
	v_mul_f32_e32 v60, v65, v125
	v_cvt_pk_bf16_f32 v58, v62, v58
	v_add_co_u32_e32 v62, vcc, s2, v156
	v_cvt_pk_bf16_f32 v59, v59, v60
	v_cvt_pk_bf16_f32 v60, v68, v63
	v_cvt_pk_bf16_f32 v61, v64, v61
	v_mul_f32_e32 v45, v45, v121
	s_nop 0
	v_addc_co_u32_e32 v63, vcc, 0, v157, vcc
	global_store_dwordx4 v[62:63], v[58:61], off
	s_mov_b64 s[2:3], 0x90000
	v_mul_f32_e32 v30, v30, v114
	v_mul_f32_e32 v58, v42, v118
	v_mul_f32_e32 v42, v47, v115
	v_mul_f32_e32 v47, v43, v119
	v_mul_f32_e32 v43, v48, v116
	v_mul_f32_e32 v48, v44, v120
	v_mul_f32_e32 v44, v49, v117
	v_cvt_pk_bf16_f32 v42, v46, v42
	v_cvt_pk_bf16_f32 v43, v43, v44
	v_cvt_pk_bf16_f32 v44, v58, v47
	v_cvt_pk_bf16_f32 v45, v48, v45
	global_store_dwordx4 v[66:67], v[42:45], off offset:256
	v_mul_f32_e32 v48, v56, v124
	v_mul_f32_e32 v49, v52, v128
	v_mul_f32_e32 v42, v54, v122
	v_mul_f32_e32 v43, v55, v123
	v_mul_f32_e32 v44, v50, v126
	v_mul_f32_e32 v45, v51, v127
	v_mul_f32_e32 v50, v57, v125
	v_cvt_pk_bf16_f32 v42, v42, v43
	v_cvt_pk_bf16_f32 v43, v48, v50
	v_add_co_u32_e32 v48, vcc, s76, v156
	v_mul_f32_e32 v51, v53, v129
	v_cvt_pk_bf16_f32 v44, v44, v45
	v_cvt_pk_bf16_f32 v45, v49, v51
	s_nop 0
	v_addc_co_u32_e32 v49, vcc, 0, v157, vcc
	global_store_dwordx4 v[48:49], v[42:45], off
	v_lshl_add_u64 v[46:47], v[156:157], 0, s[2:3]
	v_mul_f32_e32 v29, v29, v121
	v_mul_f32_e32 v42, v26, v118
	v_mul_f32_e32 v26, v31, v115
	v_mul_f32_e32 v31, v27, v119
	v_mul_f32_e32 v27, v32, v116
	v_mul_f32_e32 v32, v28, v120
	v_mul_f32_e32 v28, v33, v117
	v_cvt_pk_bf16_f32 v26, v30, v26
	v_cvt_pk_bf16_f32 v27, v27, v28
	s_mov_b64 s[2:3], 0xa0000
	v_cvt_pk_bf16_f32 v28, v42, v31
	v_cvt_pk_bf16_f32 v29, v32, v29
	global_store_dwordx4 v[46:47], v[26:29], off offset:256
	v_lshl_add_u64 v[30:31], v[156:157], 0, s[2:3]
	v_mul_f32_e32 v32, v40, v124
	v_mul_f32_e32 v26, v38, v122
	v_mul_f32_e32 v27, v39, v123
	s_mov_b32 s2, 0xa0000
	v_mul_f32_e32 v28, v34, v126
	v_mul_f32_e32 v29, v35, v127
	v_mul_f32_e32 v33, v36, v128
	v_mul_f32_e32 v34, v41, v125
	v_cvt_pk_bf16_f32 v26, v26, v27
	v_cvt_pk_bf16_f32 v27, v32, v34
	v_add_co_u32_e32 v32, vcc, s2, v156
	v_mul_f32_e32 v35, v37, v129
	v_cvt_pk_bf16_f32 v28, v28, v29
	v_cvt_pk_bf16_f32 v29, v33, v35
	s_nop 0
	v_addc_co_u32_e32 v33, vcc, 0, v157, vcc
	global_store_dwordx4 v[32:33], v[26:29], off
	v_mul_f32_e32 v14, v14, v114
	v_mul_f32_e32 v13, v13, v121
	v_mul_f32_e32 v26, v10, v118
	v_mul_f32_e32 v10, v15, v115
	v_mul_f32_e32 v15, v11, v119
	v_mul_f32_e32 v11, v16, v116
	v_mul_f32_e32 v16, v12, v120
	v_mul_f32_e32 v12, v17, v117
	v_cvt_pk_bf16_f32 v10, v14, v10
	v_cvt_pk_bf16_f32 v11, v11, v12
	s_mov_b64 s[2:3], 0xb0000
	v_cvt_pk_bf16_f32 v12, v26, v15
	v_cvt_pk_bf16_f32 v13, v16, v13
	global_store_dwordx4 v[30:31], v[10:13], off offset:256
	v_lshl_add_u64 v[14:15], v[156:157], 0, s[2:3]
	v_mul_f32_e32 v16, v24, v124
	v_mul_f32_e32 v10, v22, v122
	v_mul_f32_e32 v11, v23, v123
	s_mov_b32 s2, 0xb0000
	v_mul_f32_e32 v12, v18, v126
	v_mul_f32_e32 v13, v19, v127
	v_mul_f32_e32 v17, v20, v128
	v_mul_f32_e32 v18, v25, v125
	v_cvt_pk_bf16_f32 v10, v10, v11
	v_cvt_pk_bf16_f32 v11, v16, v18
	v_add_co_u32_e32 v16, vcc, s2, v156
	v_mul_f32_e32 v19, v21, v129
	v_cvt_pk_bf16_f32 v12, v12, v13
	v_cvt_pk_bf16_f32 v13, v17, v19
	s_nop 0
	v_addc_co_u32_e32 v17, vcc, 0, v157, vcc
	global_store_dwordx4 v[16:17], v[10:13], off
	v_mul_f32_e32 v5, v5, v121
	s_andn2_b64 vcc, exec, s[40:41]
	v_mul_f32_e32 v10, v2, v118
	v_mul_f32_e32 v2, v7, v115
	v_mul_f32_e32 v7, v3, v119
	v_mul_f32_e32 v3, v8, v116
	v_mul_f32_e32 v8, v4, v120
	v_mul_f32_e32 v4, v9, v117
	v_mul_f32_e32 v6, v6, v114
	v_cvt_pk_bf16_f32 v2, v6, v2
	v_cvt_pk_bf16_f32 v3, v3, v4
	v_cvt_pk_bf16_f32 v4, v10, v7
	v_cvt_pk_bf16_f32 v5, v8, v5
	global_store_dwordx4 v[14:15], v[2:5], off offset:256
	s_cbranch_vccnz .LBB0_87
	s_andn2_b64 vcc, exec, s[12:13]
	s_cbranch_vccnz .LBB0_86
	s_barrier
	s_branch .LBB0_86

; __device__ __forceinline__ void st8(bf16_t* p, const float (&v)[8]) { u32x4 w; w.x = pk2(v[0], v[1]); w.y = pk2(v[2], v[3]); w.z = pk2(v[4], v[5]); w.w = pk2(v[6], v[7]); *(u32x4*)p = w; }
;     __device__ __forceinline__ void operator()(const f32x4 (&acc)[2][2][4][2], const Unit& u, int wr, int wc, int fr, int fq) const {
;         const int row0 = u.pm * 256 + wr * 64 + fr, pn = u.pn;
;         if (pn < 8) {
;             bf16_t* dst = pn < 4 ? q : k; const float sc = pn < 4 ? QSCALE : 1.f;
;             const int head = (pn & 3) * 2 + (wc >> 1), i0 = 32 * (wc & 1) + 8 * fq;
; #pragma unroll
;             for (int ai = 0; ai < 2; ++ai)
; #pragma unroll
;                 for (int m = 0; m < 4; ++m) {
;                     const int row = row0 + ai * 128 + m * 16, pos = row & (SEQ - 1);
;                     const f32x4* cp = (const f32x4*)(cosT + pos * 64 + i0); const f32x4* sp = (const f32x4*)(sinT + pos * 64 + i0);
;                     const f32x4 c0 = cp[0], c1 = cp[1], s0 = sp[0], s1 = sp[1];
;                     float o1[8], o2[8];
; #pragma unroll
;                     for (int j = 0; j < 4; ++j) {
;                         const float a0 = acc[ai][0][m][0][j], b0 = acc[ai][1][m][0][j], a1 = acc[ai][0][m][1][j], b1 = acc[ai][1][m][1][j];
;                         o1[j] = (a0 * c0[j] - b0 * s0[j]) * sc; o2[j] = (b0 * c0[j] + a0 * s0[j]) * sc;
;                         o1[4 + j] = (a1 * c1[j] - b1 * s1[j]) * sc; o2[4 + j] = (b1 * c1[j] + a1 * s1[j]) * sc;
;                     }
;                     bf16_t* rp = dst + (size_t)row * AW + head * 128 + i0;
;                     st8(rp, o1); st8(rp + 64, o2);
.LBB0_355:
	s_cmp_lt_i32 s72, 4
	s_cselect_b64 vcc, -1, 0
	v_mov_b32_e32 v0, 0x3e0293ee
	v_cndmask_b32_e32 v173, 1.0, v0, vcc
	v_lshlrev_b32_e32 v0, 8, v164
	v_and_b32_e32 v0, 0xfcf00, v0
	v_mov_b32_e32 v236, v0
	v_mov_b32_e32 v239, 0
	v_mov_b32_e32 v238, v236
	v_lshl_add_u64 v[240:241], v[154:155], 0, v[238:239]
	v_lshl_add_u64 v[242:243], v[156:157], 0, v[238:239]
	global_load_dwordx4 v[186:189], v[240:241], off
	global_load_dwordx4 v[190:193], v[240:241], off offset:16
	global_load_dwordx4 v[194:197], v[242:243], off
	global_load_dwordx4 v[198:201], v[242:243], off offset:16
	v_add_u32_e32 v238, 0x1000, v236
	v_lshl_add_u64 v[240:241], v[154:155], 0, v[238:239]
	v_lshl_add_u64 v[242:243], v[156:157], 0, v[238:239]
	global_load_dwordx4 v[202:205], v[240:241], off
	global_load_dwordx4 v[206:209], v[240:241], off offset:16
	global_load_dwordx4 v[210:213], v[242:243], off
	global_load_dwordx4 v[214:217], v[242:243], off offset:16
	v_add_u32_e32 v238, 0x2000, v236
	v_lshl_add_u64 v[240:241], v[154:155], 0, v[238:239]
	v_lshl_add_u64 v[242:243], v[156:157], 0, v[238:239]
	global_load_dwordx4 v[218:221], v[240:241], off
	global_load_dwordx4 v[222:225], v[240:241], off offset:16
	global_load_dwordx4 v[226:229], v[242:243], off
	global_load_dwordx4 v[230:233], v[242:243], off offset:16
	v_lshl_add_u64 v[2:3], v[154:155], 0, v[0:1]
	v_lshl_add_u64 v[6:7], v[156:157], 0, v[0:1]
	s_and_b64 s[2:3], vcc, exec
	s_mov_b32 s2, 0xd6e4000
	s_cselect_b32 s2, s2, 0xf6e4000
	s_add_u32 s2, s22, s2
	v_mov_b32_e32 v174, v134
	v_mov_b32_e32 v175, v126
	s_addc_u32 s3, s23, 0
	s_lshl_b32 s4, s72, 1
	s_and_b32 s4, s4, 6
	s_or_b32 s4, s4, s66
	s_lshl_b32 s4, s4, 8
	s_add_u32 s2, s2, s4
	s_addc_u32 s3, s3, 0
	v_mov_b32_e32 v163, v1
	v_lshl_add_u64 v[166:167], s[2:3], 0, v[162:163]
	v_ashrrev_i32_e32 v165, 31, v164
	s_waitcnt vmcnt(8) lgkmcnt(0)
	v_mov_b32_e32 v142, v186
	v_mov_b32_e32 v143, v187
	v_mov_b32_e32 v144, v188
	v_mov_b32_e32 v145, v189
	v_mov_b32_e32 v2, v190
	v_mov_b32_e32 v3, v191
	v_mov_b32_e32 v4, v192
	v_mov_b32_e32 v5, v193
	v_mov_b32_e32 v138, v194
	v_mov_b32_e32 v139, v195
	v_mov_b32_e32 v140, v196
	v_mov_b32_e32 v141, v197
	v_mov_b32_e32 v6, v198
	v_mov_b32_e32 v7, v199
	v_mov_b32_e32 v8, v200
	v_mov_b32_e32 v9, v201
	v_add_u32_e32 v238, 0x3000, v236
	v_lshl_add_u64 v[240:241], v[154:155], 0, v[238:239]
	v_lshl_add_u64 v[242:243], v[156:157], 0, v[238:239]
	global_load_dwordx4 v[186:189], v[240:241], off
	global_load_dwordx4 v[190:193], v[240:241], off offset:16
	global_load_dwordx4 v[194:197], v[242:243], off
	global_load_dwordx4 v[198:201], v[242:243], off offset:16
	v_mov_b32_e32 v176, v142
	v_mov_b32_e32 v177, v138
	v_pk_mul_f32 v[174:175], v[174:175], v[176:177]
	v_mov_b32_e32 v138, v143
	v_sub_f32_e32 v0, v174, v175
	v_mov_b32_e32 v174, v126
	v_mov_b32_e32 v175, v134
	v_pk_mul_f32 v[174:175], v[174:175], v[176:177]
	v_mov_b32_e32 v176, v2
	v_add_f32_e32 v126, v174, v175
	v_mov_b32_e32 v174, v130
	v_mov_b32_e32 v175, v122
	v_mov_b32_e32 v177, v6
	v_pk_mul_f32 v[174:175], v[174:175], v[176:177]
	v_mul_f32_e32 v163, v173, v126
	v_sub_f32_e32 v2, v174, v175
	v_mov_b32_e32 v174, v122
	v_mov_b32_e32 v175, v130
	v_pk_mul_f32 v[174:175], v[174:175], v[176:177]
	v_mov_b32_e32 v126, v135
	v_mul_f32_e32 v185, v173, v2
	v_add_f32_e32 v2, v174, v175
	v_pk_mul_f32 v[142:143], v[126:127], v[138:139]
	v_mov_b32_e32 v134, v127
	v_mul_f32_e32 v174, v173, v2
	v_sub_f32_e32 v2, v142, v143
	v_pk_mul_f32 v[126:127], v[134:135], v[138:139]
	v_mul_f32_e32 v142, v173, v2
	v_add_f32_e32 v2, v126, v127
	v_mov_b32_e32 v122, v131
	v_mov_b32_e32 v6, v3
	v_mul_f32_e32 v126, v173, v2
	v_pk_mul_f32 v[2:3], v[122:123], v[6:7]
	v_mov_b32_e32 v130, v123
	v_sub_f32_e32 v2, v2, v3
	v_mul_f32_e32 v122, v173, v2
	v_pk_mul_f32 v[2:3], v[130:131], v[6:7]
	v_mov_b32_e32 v6, v144
	v_add_f32_e32 v2, v2, v3
	v_mul_f32_e32 v123, v173, v2
	v_mov_b32_e32 v2, v136
	v_mov_b32_e32 v3, v128
	v_mov_b32_e32 v7, v140
	v_pk_mul_f32 v[2:3], v[2:3], v[6:7]
	v_mov_b32_e32 v140, v145
	v_sub_f32_e32 v2, v2, v3
	v_mul_f32_e32 v127, v173, v2
	v_mov_b32_e32 v2, v128
	v_mov_b32_e32 v3, v136
	v_pk_mul_f32 v[2:3], v[2:3], v[6:7]
	v_mov_b32_e32 v6, v4
	v_add_f32_e32 v2, v2, v3
	v_mul_f32_e32 v130, v173, v2
	v_mov_b32_e32 v2, v132
	v_mov_b32_e32 v3, v124
	v_mov_b32_e32 v7, v8
	v_pk_mul_f32 v[2:3], v[2:3], v[6:7]
	v_mov_b32_e32 v128, v137
	v_sub_f32_e32 v2, v2, v3
	v_mul_f32_e32 v131, v173, v2
	v_mov_b32_e32 v2, v124
	v_mov_b32_e32 v3, v132
	v_pk_mul_f32 v[2:3], v[2:3], v[6:7]
	v_mov_b32_e32 v136, v129
	v_add_f32_e32 v2, v2, v3
	v_mul_f32_e32 v134, v173, v2
	v_pk_mul_f32 v[2:3], v[128:129], v[140:141]
	v_mov_b32_e32 v124, v133
	v_sub_f32_e32 v2, v2, v3
	v_mul_f32_e32 v4, v173, v2
	v_pk_mul_f32 v[2:3], v[136:137], v[140:141]
	v_mov_b32_e32 v8, v5
	v_add_f32_e32 v2, v2, v3
	v_mul_f32_e32 v128, v173, v2
	v_pk_mul_f32 v[2:3], v[124:125], v[8:9]
	v_mov_b32_e32 v132, v125
	v_sub_f32_e32 v2, v2, v3
	v_mul_f32_e32 v5, v173, v2
	v_pk_mul_f32 v[2:3], v[132:133], v[8:9]
	v_mul_f32_e32 v0, v173, v0
	v_add_f32_e32 v2, v2, v3
	v_mul_f32_e32 v8, v173, v2
	v_lshlrev_b64 v[2:3], 11, v[164:165]
	v_lshl_add_u64 v[6:7], v[166:167], 0, v[2:3]
	v_cvt_pk_bf16_f32 v3, v127, v4
	v_cvt_pk_bf16_f32 v2, v0, v142
	v_cvt_pk_bf16_f32 v4, v185, v122
	v_cvt_pk_bf16_f32 v5, v131, v5
	global_store_dwordx4 v[6:7], v[2:5], off
	v_mov_b32_e32 v132, v118
	v_mov_b32_e32 v133, v110
	v_cvt_pk_bf16_f32 v3, v130, v128
	v_or_b32_e32 v130, 16, v164
	v_lshlrev_b32_e32 v0, 8, v130
	v_cvt_pk_bf16_f32 v2, v163, v126
	v_and_b32_e32 v0, 0xfdf00, v0
	v_cvt_pk_bf16_f32 v4, v174, v123
	v_cvt_pk_bf16_f32 v5, v134, v8
	global_store_dwordx4 v[6:7], v[2:5], off offset:128
	v_lshl_add_u64 v[6:7], v[156:157], 0, v[0:1]
	v_ashrrev_i32_e32 v131, 31, v130
	v_lshl_add_u64 v[2:3], v[154:155], 0, v[0:1]
	s_waitcnt vmcnt(10) lgkmcnt(0)
; __device__ __forceinline__ void st8(bf16_t* p, const float (&v)[8]) { u32x4 w; w.x = pk2(v[0], v[1]); w.y = pk2(v[2], v[3]); w.z = pk2(v[4], v[5]); w.w = pk2(v[6], v[7]); *(u32x4*)p = w; }
;     __device__ __forceinline__ void operator()(const f32x4 (&acc)[2][2][4][2], const Unit& u, int wr, int wc, int fr, int fq) const {
;     ...
; #pragma unroll
;             for (int ai = 0; ai < 2; ++ai)
; #pragma unroll
;                 for (int m = 0; m < 4; ++m) {
;                     const int row = row0 + ai * 128 + m * 16, pos = row & (SEQ - 1);
;                     const f32x4* cp = (const f32x4*)(cosT + pos * 64 + i0); const f32x4* sp = (const f32x4*)(sinT + pos * 64 + i0);
;                     const f32x4 c0 = cp[0], c1 = cp[1], s0 = sp[0], s1 = sp[1];
;                     float o1[8], o2[8];
; #pragma unroll
;                     for (int j = 0; j < 4; ++j) {
;                         const float a0 = acc[ai][0][m][0][j], b0 = acc[ai][1][m][0][j], a1 = acc[ai][0][m][1][j], b1 = acc[ai][1][m][1][j];
;                         o1[j] = (a0 * c0[j] - b0 * s0[j]) * sc; o2[j] = (b0 * c0[j] + a0 * s0[j]) * sc;
;                         o1[4 + j] = (a1 * c1[j] - b1 * s1[j]) * sc; o2[4 + j] = (b1 * c1[j] + a1 * s1[j]) * sc;
;                     }
;                     bf16_t* rp = dst + (size_t)row * AW + head * 128 + i0;
;                     st8(rp, o1); st8(rp + 64, o2);
	v_mov_b32_e32 v126, v202
	v_mov_b32_e32 v127, v203
	v_mov_b32_e32 v128, v204
	v_mov_b32_e32 v129, v205
	v_mov_b32_e32 v2, v206
	v_mov_b32_e32 v3, v207
	v_mov_b32_e32 v4, v208
	v_mov_b32_e32 v5, v209
	v_mov_b32_e32 v122, v210
	v_mov_b32_e32 v123, v211
	v_mov_b32_e32 v124, v212
	v_mov_b32_e32 v125, v213
	v_mov_b32_e32 v6, v214
	v_mov_b32_e32 v7, v215
	v_mov_b32_e32 v8, v216
	v_mov_b32_e32 v9, v217
	v_add_u32_e32 v238, 0x8000, v236
	v_lshl_add_u64 v[240:241], v[154:155], 0, v[238:239]
	v_lshl_add_u64 v[242:243], v[156:157], 0, v[238:239]
	global_load_dwordx4 v[202:205], v[240:241], off
	global_load_dwordx4 v[206:209], v[240:241], off offset:16
	global_load_dwordx4 v[210:213], v[242:243], off
	global_load_dwordx4 v[214:217], v[242:243], off offset:16
	v_mov_b32_e32 v134, v126
	v_mov_b32_e32 v135, v122
	v_pk_mul_f32 v[132:133], v[132:133], v[134:135]
	v_mov_b32_e32 v122, v127
	v_sub_f32_e32 v0, v132, v133
	v_mov_b32_e32 v132, v110
	v_mov_b32_e32 v133, v118
	v_pk_mul_f32 v[132:133], v[132:133], v[134:135]
	v_mov_b32_e32 v134, v2
	v_add_f32_e32 v110, v132, v133
	v_mov_b32_e32 v132, v114
	v_mov_b32_e32 v133, v106
	v_mov_b32_e32 v135, v6
	v_pk_mul_f32 v[132:133], v[132:133], v[134:135]
	v_mul_f32_e32 v136, v173, v110
	v_sub_f32_e32 v2, v132, v133
	v_mov_b32_e32 v132, v106
	v_mov_b32_e32 v133, v114
	v_pk_mul_f32 v[132:133], v[132:133], v[134:135]
	v_mov_b32_e32 v110, v119
	v_mul_f32_e32 v137, v173, v2
	v_add_f32_e32 v2, v132, v133
	v_pk_mul_f32 v[126:127], v[110:111], v[122:123]
	v_mov_b32_e32 v118, v111
	v_mul_f32_e32 v132, v173, v2
	v_sub_f32_e32 v2, v126, v127
	v_pk_mul_f32 v[110:111], v[118:119], v[122:123]
	v_mul_f32_e32 v126, v173, v2
	v_add_f32_e32 v2, v110, v111
	v_mov_b32_e32 v106, v115
	v_mov_b32_e32 v6, v3
	v_mul_f32_e32 v110, v173, v2
	v_pk_mul_f32 v[2:3], v[106:107], v[6:7]
	v_mov_b32_e32 v114, v107
	v_sub_f32_e32 v2, v2, v3
	v_mul_f32_e32 v106, v173, v2
	v_pk_mul_f32 v[2:3], v[114:115], v[6:7]
	v_mov_b32_e32 v6, v128
	v_add_f32_e32 v2, v2, v3
	v_mul_f32_e32 v107, v173, v2
	v_mov_b32_e32 v2, v120
	v_mov_b32_e32 v3, v112
	v_mov_b32_e32 v7, v124
	v_pk_mul_f32 v[2:3], v[2:3], v[6:7]
	v_mov_b32_e32 v124, v129
	v_sub_f32_e32 v2, v2, v3
	v_mul_f32_e32 v111, v173, v2
	v_mov_b32_e32 v2, v112
	v_mov_b32_e32 v3, v120
	v_pk_mul_f32 v[2:3], v[2:3], v[6:7]
	v_mov_b32_e32 v6, v4
	v_add_f32_e32 v2, v2, v3
	v_mul_f32_e32 v114, v173, v2
	v_mov_b32_e32 v2, v116
	v_mov_b32_e32 v3, v108
	v_mov_b32_e32 v7, v8
	v_pk_mul_f32 v[2:3], v[2:3], v[6:7]
	v_mov_b32_e32 v112, v121
	v_sub_f32_e32 v2, v2, v3
	v_mul_f32_e32 v115, v173, v2
	v_mov_b32_e32 v2, v108
	v_mov_b32_e32 v3, v116
	v_pk_mul_f32 v[2:3], v[2:3], v[6:7]
	v_mov_b32_e32 v120, v113
	v_add_f32_e32 v2, v2, v3
	v_mul_f32_e32 v118, v173, v2
	v_pk_mul_f32 v[2:3], v[112:113], v[124:125]
	v_mov_b32_e32 v108, v117
	v_sub_f32_e32 v2, v2, v3
	v_mul_f32_e32 v4, v173, v2
	v_pk_mul_f32 v[2:3], v[120:121], v[124:125]
	v_mov_b32_e32 v8, v5
	v_add_f32_e32 v2, v2, v3
	v_mul_f32_e32 v112, v173, v2
	v_pk_mul_f32 v[2:3], v[108:109], v[8:9]
	v_mov_b32_e32 v116, v109
	v_sub_f32_e32 v2, v2, v3
	v_mul_f32_e32 v5, v173, v2
	v_pk_mul_f32 v[2:3], v[116:117], v[8:9]
	v_mul_f32_e32 v0, v173, v0
	v_add_f32_e32 v2, v2, v3
	v_mul_f32_e32 v8, v173, v2
	v_lshlrev_b64 v[2:3], 11, v[130:131]
	v_lshl_add_u64 v[6:7], v[166:167], 0, v[2:3]
	v_cvt_pk_bf16_f32 v3, v111, v4
	v_cvt_pk_bf16_f32 v2, v0, v126
	v_cvt_pk_bf16_f32 v4, v137, v106
	v_cvt_pk_bf16_f32 v5, v115, v5
	global_store_dwordx4 v[6:7], v[2:5], off
	v_mov_b32_e32 v116, v102
	v_mov_b32_e32 v117, v94
	v_cvt_pk_bf16_f32 v3, v114, v112
	v_or_b32_e32 v114, 32, v164
	v_lshlrev_b32_e32 v0, 8, v114
	v_and_b32_e32 v0, 0xfef00, v0
	v_cvt_pk_bf16_f32 v2, v136, v110
	v_cvt_pk_bf16_f32 v4, v132, v107
	v_cvt_pk_bf16_f32 v5, v118, v8
	global_store_dwordx4 v[6:7], v[2:5], off offset:128
	v_lshl_add_u64 v[6:7], v[154:155], 0, v[0:1]
	v_lshl_add_u64 v[110:111], v[156:157], 0, v[0:1]
	v_ashrrev_i32_e32 v115, 31, v114
	s_waitcnt vmcnt(12) lgkmcnt(0)
	v_mov_b32_e32 v2, v218
	v_mov_b32_e32 v3, v219
	v_mov_b32_e32 v4, v220
	v_mov_b32_e32 v5, v221
	v_mov_b32_e32 v6, v222
	v_mov_b32_e32 v7, v223
	v_mov_b32_e32 v8, v224
	v_mov_b32_e32 v9, v225
	v_mov_b32_e32 v106, v226
	v_mov_b32_e32 v107, v227
	v_mov_b32_e32 v108, v228
	v_mov_b32_e32 v109, v229
	v_mov_b32_e32 v110, v230
	v_mov_b32_e32 v111, v231
	v_mov_b32_e32 v112, v232
	v_mov_b32_e32 v113, v233
	v_add_u32_e32 v238, 0x9000, v236
	v_lshl_add_u64 v[240:241], v[154:155], 0, v[238:239]
	v_lshl_add_u64 v[242:243], v[156:157], 0, v[238:239]
	global_load_dwordx4 v[218:221], v[240:241], off
	global_load_dwordx4 v[222:225], v[240:241], off offset:16
	global_load_dwordx4 v[226:229], v[242:243], off
	global_load_dwordx4 v[230:233], v[242:243], off offset:16
	v_mov_b32_e32 v118, v2
	v_mov_b32_e32 v119, v106
	v_pk_mul_f32 v[116:117], v[116:117], v[118:119]
	v_mov_b32_e32 v106, v3
	v_sub_f32_e32 v0, v116, v117
	v_mov_b32_e32 v116, v94
	v_mov_b32_e32 v117, v102
	v_pk_mul_f32 v[116:117], v[116:117], v[118:119]
	v_mov_b32_e32 v118, v6
	v_add_f32_e32 v2, v116, v117
	v_mov_b32_e32 v116, v98
	v_mov_b32_e32 v117, v90
	v_mov_b32_e32 v119, v110
	v_pk_mul_f32 v[116:117], v[116:117], v[118:119]
	v_mul_f32_e32 v120, v173, v2
	v_sub_f32_e32 v2, v116, v117
	v_mov_b32_e32 v116, v90
	v_mov_b32_e32 v117, v98
	v_pk_mul_f32 v[116:117], v[116:117], v[118:119]
	v_mul_f32_e32 v121, v173, v2
	v_add_f32_e32 v2, v116, v117
	v_mov_b32_e32 v94, v103
	v_mul_f32_e32 v116, v173, v2
	v_pk_mul_f32 v[2:3], v[94:95], v[106:107]
	v_mov_b32_e32 v102, v95
	v_sub_f32_e32 v2, v2, v3
	v_mul_f32_e32 v94, v173, v2
	v_pk_mul_f32 v[2:3], v[102:103], v[106:107]
	v_mov_b32_e32 v90, v99
	v_add_f32_e32 v2, v2, v3
; __device__ __forceinline__ void st8(bf16_t* p, const float (&v)[8]) { u32x4 w; w.x = pk2(v[0], v[1]); w.y = pk2(v[2], v[3]); w.z = pk2(v[4], v[5]); w.w = pk2(v[6], v[7]); *(u32x4*)p = w; }
;     __device__ __forceinline__ void operator()(const f32x4 (&acc)[2][2][4][2], const Unit& u, int wr, int wc, int fr, int fq) const {
;     ...
; #pragma unroll
;             for (int ai = 0; ai < 2; ++ai)
; #pragma unroll
;                 for (int m = 0; m < 4; ++m) {
;                     const int row = row0 + ai * 128 + m * 16, pos = row & (SEQ - 1);
;                     const f32x4* cp = (const f32x4*)(cosT + pos * 64 + i0); const f32x4* sp = (const f32x4*)(sinT + pos * 64 + i0);
;                     const f32x4 c0 = cp[0], c1 = cp[1], s0 = sp[0], s1 = sp[1];
;                     float o1[8], o2[8];
; #pragma unroll
;                     for (int j = 0; j < 4; ++j) {
;                         const float a0 = acc[ai][0][m][0][j], b0 = acc[ai][1][m][0][j], a1 = acc[ai][0][m][1][j], b1 = acc[ai][1][m][1][j];
;                         o1[j] = (a0 * c0[j] - b0 * s0[j]) * sc; o2[j] = (b0 * c0[j] + a0 * s0[j]) * sc;
;                         o1[4 + j] = (a1 * c1[j] - b1 * s1[j]) * sc; o2[4 + j] = (b1 * c1[j] + a1 * s1[j]) * sc;
;                     }
;                     bf16_t* rp = dst + (size_t)row * AW + head * 128 + i0;
;                     st8(rp, o1); st8(rp + 64, o2);
	v_mov_b32_e32 v110, v7
	v_mul_f32_e32 v95, v173, v2
	v_pk_mul_f32 v[2:3], v[90:91], v[110:111]
	v_mov_b32_e32 v98, v91
	v_sub_f32_e32 v2, v2, v3
	v_mul_f32_e32 v90, v173, v2
	v_pk_mul_f32 v[2:3], v[98:99], v[110:111]
	v_mov_b32_e32 v6, v4
	v_add_f32_e32 v2, v2, v3
	v_mul_f32_e32 v91, v173, v2
	v_mov_b32_e32 v2, v104
	v_mov_b32_e32 v3, v96
	v_mov_b32_e32 v7, v108
	v_pk_mul_f32 v[2:3], v[2:3], v[6:7]
	v_mov_b32_e32 v108, v5
	v_sub_f32_e32 v2, v2, v3
	v_mul_f32_e32 v4, v173, v2
	v_mov_b32_e32 v2, v96
	v_mov_b32_e32 v3, v104
	v_pk_mul_f32 v[2:3], v[2:3], v[6:7]
	v_mov_b32_e32 v6, v8
	v_add_f32_e32 v2, v2, v3
	v_mul_f32_e32 v98, v173, v2
	v_mov_b32_e32 v2, v100
	v_mov_b32_e32 v3, v92
	v_mov_b32_e32 v7, v112
	v_pk_mul_f32 v[2:3], v[2:3], v[6:7]
	v_mov_b32_e32 v96, v105
	v_sub_f32_e32 v2, v2, v3
	v_mul_f32_e32 v8, v173, v2
	v_mov_b32_e32 v2, v92
	v_mov_b32_e32 v3, v100
	v_pk_mul_f32 v[2:3], v[2:3], v[6:7]
	v_mov_b32_e32 v104, v97
	v_add_f32_e32 v2, v2, v3
	v_mul_f32_e32 v99, v173, v2
	v_pk_mul_f32 v[2:3], v[96:97], v[108:109]
	v_mov_b32_e32 v92, v101
	v_sub_f32_e32 v2, v2, v3
	v_mul_f32_e32 v5, v173, v2
	v_pk_mul_f32 v[2:3], v[104:105], v[108:109]
	v_mov_b32_e32 v112, v9
	v_add_f32_e32 v2, v2, v3
	v_mul_f32_e32 v96, v173, v2
	v_pk_mul_f32 v[2:3], v[92:93], v[112:113]
	v_mov_b32_e32 v100, v93
	v_sub_f32_e32 v2, v2, v3
	v_mul_f32_e32 v9, v173, v2
	v_pk_mul_f32 v[2:3], v[100:101], v[112:113]
	v_mul_f32_e32 v0, v173, v0
	v_add_f32_e32 v2, v2, v3
	v_mul_f32_e32 v92, v173, v2
	v_lshlrev_b64 v[2:3], 11, v[114:115]
	v_lshl_add_u64 v[6:7], v[166:167], 0, v[2:3]
	v_cvt_pk_bf16_f32 v3, v4, v5
	v_cvt_pk_bf16_f32 v2, v0, v94
	v_cvt_pk_bf16_f32 v4, v121, v90
	v_cvt_pk_bf16_f32 v5, v8, v9
	global_store_dwordx4 v[6:7], v[2:5], off
	v_mov_b32_e32 v100, v86
	v_mov_b32_e32 v101, v78
	v_cvt_pk_bf16_f32 v3, v98, v96
	v_or_b32_e32 v98, 48, v164
	v_lshlrev_b32_e32 v0, 8, v98
	v_and_b32_e32 v0, 0xfff00, v0
	v_cvt_pk_bf16_f32 v2, v120, v95
	v_cvt_pk_bf16_f32 v4, v116, v91
	v_cvt_pk_bf16_f32 v5, v99, v92
	global_store_dwordx4 v[6:7], v[2:5], off offset:128
	v_lshl_add_u64 v[6:7], v[154:155], 0, v[0:1]
	v_lshl_add_u64 v[94:95], v[156:157], 0, v[0:1]
	v_ashrrev_i32_e32 v99, 31, v98
	s_waitcnt vmcnt(14) lgkmcnt(0)
	v_mov_b32_e32 v2, v186
	v_mov_b32_e32 v3, v187
	v_mov_b32_e32 v4, v188
	v_mov_b32_e32 v5, v189
	v_mov_b32_e32 v6, v190
	v_mov_b32_e32 v7, v191
	v_mov_b32_e32 v8, v192
	v_mov_b32_e32 v9, v193
	v_mov_b32_e32 v90, v194
	v_mov_b32_e32 v91, v195
	v_mov_b32_e32 v92, v196
	v_mov_b32_e32 v93, v197
	v_mov_b32_e32 v94, v198
	v_mov_b32_e32 v95, v199
	v_mov_b32_e32 v96, v200
	v_mov_b32_e32 v97, v201
	v_add_u32_e32 v238, 0xa000, v236
	v_lshl_add_u64 v[240:241], v[154:155], 0, v[238:239]
	v_lshl_add_u64 v[242:243], v[156:157], 0, v[238:239]
	global_load_dwordx4 v[186:189], v[240:241], off
	global_load_dwordx4 v[190:193], v[240:241], off offset:16
	global_load_dwordx4 v[194:197], v[242:243], off
	global_load_dwordx4 v[198:201], v[242:243], off offset:16
	v_mov_b32_e32 v102, v2
	v_mov_b32_e32 v103, v90
	v_pk_mul_f32 v[100:101], v[100:101], v[102:103]
	v_mov_b32_e32 v90, v3
	v_sub_f32_e32 v0, v100, v101
	v_mov_b32_e32 v100, v78
	v_mov_b32_e32 v101, v86
	v_pk_mul_f32 v[100:101], v[100:101], v[102:103]
	v_mov_b32_e32 v102, v6
	v_add_f32_e32 v2, v100, v101
	v_mov_b32_e32 v100, v82
	v_mov_b32_e32 v101, v74
	v_mov_b32_e32 v103, v94
	v_pk_mul_f32 v[100:101], v[100:101], v[102:103]
	v_mul_f32_e32 v104, v173, v2
	v_sub_f32_e32 v2, v100, v101
	v_mov_b32_e32 v100, v74
	v_mov_b32_e32 v101, v82
	v_pk_mul_f32 v[100:101], v[100:101], v[102:103]
	v_mul_f32_e32 v105, v173, v2
	v_add_f32_e32 v2, v100, v101
	v_mov_b32_e32 v78, v87
	v_mul_f32_e32 v100, v173, v2
	v_pk_mul_f32 v[2:3], v[78:79], v[90:91]
	v_mov_b32_e32 v86, v79
	v_sub_f32_e32 v2, v2, v3
	v_mul_f32_e32 v78, v173, v2
	v_pk_mul_f32 v[2:3], v[86:87], v[90:91]
	v_mov_b32_e32 v74, v83
	v_add_f32_e32 v2, v2, v3
	v_mov_b32_e32 v94, v7
	v_mul_f32_e32 v79, v173, v2
	v_pk_mul_f32 v[2:3], v[74:75], v[94:95]
	v_mov_b32_e32 v82, v75
	v_sub_f32_e32 v2, v2, v3
	v_mul_f32_e32 v74, v173, v2
	v_pk_mul_f32 v[2:3], v[82:83], v[94:95]
	v_mov_b32_e32 v6, v4
	v_add_f32_e32 v2, v2, v3
	v_mul_f32_e32 v75, v173, v2
	v_mov_b32_e32 v2, v88
	v_mov_b32_e32 v3, v80
	v_mov_b32_e32 v7, v92
	v_pk_mul_f32 v[2:3], v[2:3], v[6:7]
	v_mov_b32_e32 v92, v5
	v_sub_f32_e32 v2, v2, v3
	v_mul_f32_e32 v4, v173, v2
	v_mov_b32_e32 v2, v80
	v_mov_b32_e32 v3, v88
	v_pk_mul_f32 v[2:3], v[2:3], v[6:7]
	v_mov_b32_e32 v6, v8
	v_add_f32_e32 v2, v2, v3
	v_mul_f32_e32 v82, v173, v2
	v_mov_b32_e32 v2, v84
	v_mov_b32_e32 v3, v76
	v_mov_b32_e32 v7, v96
	v_pk_mul_f32 v[2:3], v[2:3], v[6:7]
	v_mov_b32_e32 v80, v89
	v_sub_f32_e32 v2, v2, v3
	v_mul_f32_e32 v8, v173, v2
	v_mov_b32_e32 v2, v76
	v_mov_b32_e32 v3, v84
	v_pk_mul_f32 v[2:3], v[2:3], v[6:7]
	v_mov_b32_e32 v88, v81
	v_add_f32_e32 v2, v2, v3
	v_mul_f32_e32 v83, v173, v2
	v_pk_mul_f32 v[2:3], v[80:81], v[92:93]
	v_mov_b32_e32 v76, v85
	v_sub_f32_e32 v2, v2, v3
	v_mul_f32_e32 v5, v173, v2
	v_pk_mul_f32 v[2:3], v[88:89], v[92:93]
	v_mov_b32_e32 v96, v9
	v_add_f32_e32 v2, v2, v3
	v_mul_f32_e32 v80, v173, v2
	v_pk_mul_f32 v[2:3], v[76:77], v[96:97]
	v_mov_b32_e32 v84, v77
	v_sub_f32_e32 v2, v2, v3
	v_mul_f32_e32 v9, v173, v2
	v_pk_mul_f32 v[2:3], v[84:85], v[96:97]
	v_mul_f32_e32 v0, v173, v0
	v_add_f32_e32 v2, v2, v3
	v_mul_f32_e32 v76, v173, v2
	v_lshlrev_b64 v[2:3], 11, v[98:99]
	v_lshl_add_u64 v[6:7], v[166:167], 0, v[2:3]
	v_cvt_pk_bf16_f32 v3, v4, v5
	v_cvt_pk_bf16_f32 v2, v0, v78
	v_cvt_pk_bf16_f32 v4, v105, v74
	v_cvt_pk_bf16_f32 v5, v8, v9
	global_store_dwordx4 v[6:7], v[2:5], off
	v_mov_b32_e32 v84, v70
	v_mov_b32_e32 v85, v62
	v_cvt_pk_bf16_f32 v3, v82, v80
	v_add_u32_e32 v82, 0x80, v164
	v_lshlrev_b32_e32 v0, 8, v82
	v_and_b32_e32 v0, 0xfcf00, v0
	v_cvt_pk_bf16_f32 v2, v104, v79
	v_cvt_pk_bf16_f32 v4, v100, v75
	v_cvt_pk_bf16_f32 v5, v83, v76
	global_store_dwordx4 v[6:7], v[2:5], off offset:128
	v_lshl_add_u64 v[6:7], v[154:155], 0, v[0:1]
	v_lshl_add_u64 v[78:79], v[156:157], 0, v[0:1]
	v_ashrrev_i32_e32 v83, 31, v82
	s_waitcnt vmcnt(14) lgkmcnt(0)
; __device__ __forceinline__ void st8(bf16_t* p, const float (&v)[8]) { u32x4 w; w.x = pk2(v[0], v[1]); w.y = pk2(v[2], v[3]); w.z = pk2(v[4], v[5]); w.w = pk2(v[6], v[7]); *(u32x4*)p = w; }
;     __device__ __forceinline__ void operator()(const f32x4 (&acc)[2][2][4][2], const Unit& u, int wr, int wc, int fr, int fq) const {
;     ...
; #pragma unroll
;             for (int ai = 0; ai < 2; ++ai)
; #pragma unroll
;                 for (int m = 0; m < 4; ++m) {
;                     const int row = row0 + ai * 128 + m * 16, pos = row & (SEQ - 1);
;                     const f32x4* cp = (const f32x4*)(cosT + pos * 64 + i0); const f32x4* sp = (const f32x4*)(sinT + pos * 64 + i0);
;                     const f32x4 c0 = cp[0], c1 = cp[1], s0 = sp[0], s1 = sp[1];
;                     float o1[8], o2[8];
; #pragma unroll
;                     for (int j = 0; j < 4; ++j) {
;                         const float a0 = acc[ai][0][m][0][j], b0 = acc[ai][1][m][0][j], a1 = acc[ai][0][m][1][j], b1 = acc[ai][1][m][1][j];
;                         o1[j] = (a0 * c0[j] - b0 * s0[j]) * sc; o2[j] = (b0 * c0[j] + a0 * s0[j]) * sc;
;                         o1[4 + j] = (a1 * c1[j] - b1 * s1[j]) * sc; o2[4 + j] = (b1 * c1[j] + a1 * s1[j]) * sc;
;                     }
;                     bf16_t* rp = dst + (size_t)row * AW + head * 128 + i0;
;                     st8(rp, o1); st8(rp + 64, o2);
	v_mov_b32_e32 v2, v202
	v_mov_b32_e32 v3, v203
	v_mov_b32_e32 v4, v204
	v_mov_b32_e32 v5, v205
	v_mov_b32_e32 v6, v206
	v_mov_b32_e32 v7, v207
	v_mov_b32_e32 v8, v208
	v_mov_b32_e32 v9, v209
	v_mov_b32_e32 v74, v210
	v_mov_b32_e32 v75, v211
	v_mov_b32_e32 v76, v212
	v_mov_b32_e32 v77, v213
	v_mov_b32_e32 v78, v214
	v_mov_b32_e32 v79, v215
	v_mov_b32_e32 v80, v216
	v_mov_b32_e32 v81, v217
	v_add_u32_e32 v238, 0xb000, v236
	v_lshl_add_u64 v[240:241], v[154:155], 0, v[238:239]
	v_lshl_add_u64 v[242:243], v[156:157], 0, v[238:239]
	global_load_dwordx4 v[202:205], v[240:241], off
	global_load_dwordx4 v[206:209], v[240:241], off offset:16
	global_load_dwordx4 v[210:213], v[242:243], off
	global_load_dwordx4 v[214:217], v[242:243], off offset:16
	v_mov_b32_e32 v86, v2
	v_mov_b32_e32 v87, v74
	v_pk_mul_f32 v[84:85], v[84:85], v[86:87]
	v_mov_b32_e32 v74, v3
	v_sub_f32_e32 v0, v84, v85
	v_mov_b32_e32 v84, v62
	v_mov_b32_e32 v85, v70
	v_pk_mul_f32 v[84:85], v[84:85], v[86:87]
	v_mov_b32_e32 v86, v6
	v_add_f32_e32 v2, v84, v85
	v_mov_b32_e32 v84, v66
	v_mov_b32_e32 v85, v58
	v_mov_b32_e32 v87, v78
	v_pk_mul_f32 v[84:85], v[84:85], v[86:87]
	v_mul_f32_e32 v88, v173, v2
	v_sub_f32_e32 v2, v84, v85
	v_mov_b32_e32 v84, v58
	v_mov_b32_e32 v85, v66
	v_pk_mul_f32 v[84:85], v[84:85], v[86:87]
	v_mul_f32_e32 v89, v173, v2
	v_add_f32_e32 v2, v84, v85
	v_mov_b32_e32 v62, v71
	v_mul_f32_e32 v84, v173, v2
	v_pk_mul_f32 v[2:3], v[62:63], v[74:75]
	v_mov_b32_e32 v70, v63
	v_sub_f32_e32 v2, v2, v3
	v_mul_f32_e32 v62, v173, v2
	v_pk_mul_f32 v[2:3], v[70:71], v[74:75]
	v_mov_b32_e32 v58, v67
	v_add_f32_e32 v2, v2, v3
	v_mov_b32_e32 v78, v7
	v_mul_f32_e32 v63, v173, v2
	v_pk_mul_f32 v[2:3], v[58:59], v[78:79]
	v_mov_b32_e32 v66, v59
	v_sub_f32_e32 v2, v2, v3
	v_mul_f32_e32 v58, v173, v2
	v_pk_mul_f32 v[2:3], v[66:67], v[78:79]
	v_mov_b32_e32 v6, v4
	v_add_f32_e32 v2, v2, v3
	v_mul_f32_e32 v59, v173, v2
	v_mov_b32_e32 v2, v72
	v_mov_b32_e32 v3, v64
	v_mov_b32_e32 v7, v76
	v_pk_mul_f32 v[2:3], v[2:3], v[6:7]
	v_mov_b32_e32 v76, v5
	v_sub_f32_e32 v2, v2, v3
	v_mul_f32_e32 v4, v173, v2
	v_mov_b32_e32 v2, v64
	v_mov_b32_e32 v3, v72
	v_pk_mul_f32 v[2:3], v[2:3], v[6:7]
	v_mov_b32_e32 v6, v8
	v_add_f32_e32 v2, v2, v3
	v_mul_f32_e32 v66, v173, v2
	v_mov_b32_e32 v2, v68
	v_mov_b32_e32 v3, v60
	v_mov_b32_e32 v7, v80
	v_pk_mul_f32 v[2:3], v[2:3], v[6:7]
	v_mov_b32_e32 v64, v73
	v_sub_f32_e32 v2, v2, v3
	v_mul_f32_e32 v8, v173, v2
	v_mov_b32_e32 v2, v60
	v_mov_b32_e32 v3, v68
	v_pk_mul_f32 v[2:3], v[2:3], v[6:7]
	v_mov_b32_e32 v72, v65
	v_add_f32_e32 v2, v2, v3
	v_mul_f32_e32 v67, v173, v2
	v_pk_mul_f32 v[2:3], v[64:65], v[76:77]
	v_mov_b32_e32 v60, v69
	v_sub_f32_e32 v2, v2, v3
	v_mul_f32_e32 v5, v173, v2
	v_pk_mul_f32 v[2:3], v[72:73], v[76:77]
	v_mov_b32_e32 v80, v9
	v_add_f32_e32 v2, v2, v3
	v_mul_f32_e32 v64, v173, v2
	v_pk_mul_f32 v[2:3], v[60:61], v[80:81]
	v_mov_b32_e32 v68, v61
	v_sub_f32_e32 v2, v2, v3
	v_mul_f32_e32 v9, v173, v2
	v_pk_mul_f32 v[2:3], v[68:69], v[80:81]
	v_mul_f32_e32 v0, v173, v0
	v_add_f32_e32 v2, v2, v3
	v_mul_f32_e32 v60, v173, v2
	v_lshlrev_b64 v[2:3], 11, v[82:83]
	v_lshl_add_u64 v[6:7], v[166:167], 0, v[2:3]
	v_cvt_pk_bf16_f32 v3, v4, v5
	v_cvt_pk_bf16_f32 v2, v0, v62
	v_cvt_pk_bf16_f32 v4, v89, v58
	v_cvt_pk_bf16_f32 v5, v8, v9
	global_store_dwordx4 v[6:7], v[2:5], off
	v_mov_b32_e32 v68, v54
	v_mov_b32_e32 v69, v46
	v_cvt_pk_bf16_f32 v3, v66, v64
	v_add_u32_e32 v66, 0x90, v164
	v_lshlrev_b32_e32 v0, 8, v66
	v_and_b32_e32 v0, 0xfdf00, v0
	v_cvt_pk_bf16_f32 v2, v88, v63
	v_cvt_pk_bf16_f32 v4, v84, v59
	v_cvt_pk_bf16_f32 v5, v67, v60
	global_store_dwordx4 v[6:7], v[2:5], off offset:128
	v_lshl_add_u64 v[6:7], v[154:155], 0, v[0:1]
	v_lshl_add_u64 v[62:63], v[156:157], 0, v[0:1]
	v_ashrrev_i32_e32 v67, 31, v66
	s_waitcnt vmcnt(14) lgkmcnt(0)
	v_mov_b32_e32 v2, v218
	v_mov_b32_e32 v3, v219
	v_mov_b32_e32 v4, v220
	v_mov_b32_e32 v5, v221
	v_mov_b32_e32 v6, v222
	v_mov_b32_e32 v7, v223
	v_mov_b32_e32 v8, v224
	v_mov_b32_e32 v9, v225
	v_mov_b32_e32 v58, v226
	v_mov_b32_e32 v59, v227
	v_mov_b32_e32 v60, v228
	v_mov_b32_e32 v61, v229
	v_mov_b32_e32 v62, v230
	v_mov_b32_e32 v63, v231
	v_mov_b32_e32 v64, v232
	v_mov_b32_e32 v65, v233
	v_mov_b32_e32 v70, v2
	v_mov_b32_e32 v71, v58
	v_pk_mul_f32 v[68:69], v[68:69], v[70:71]
	v_mov_b32_e32 v58, v3
	v_sub_f32_e32 v0, v68, v69
	v_mov_b32_e32 v68, v46
	v_mov_b32_e32 v69, v54
	v_pk_mul_f32 v[68:69], v[68:69], v[70:71]
	v_mov_b32_e32 v70, v6
	v_add_f32_e32 v2, v68, v69
	v_mov_b32_e32 v68, v50
	v_mov_b32_e32 v69, v42
	v_mov_b32_e32 v71, v62
	v_pk_mul_f32 v[68:69], v[68:69], v[70:71]
	v_mul_f32_e32 v72, v173, v2
	v_sub_f32_e32 v2, v68, v69
	v_mov_b32_e32 v68, v42
	v_mov_b32_e32 v69, v50
	v_pk_mul_f32 v[68:69], v[68:69], v[70:71]
	v_mul_f32_e32 v73, v173, v2
	v_add_f32_e32 v2, v68, v69
	v_mov_b32_e32 v46, v55
	v_mul_f32_e32 v68, v173, v2
	v_pk_mul_f32 v[2:3], v[46:47], v[58:59]
	v_mov_b32_e32 v54, v47
	v_sub_f32_e32 v2, v2, v3
	v_mul_f32_e32 v46, v173, v2
	v_pk_mul_f32 v[2:3], v[54:55], v[58:59]
	v_mov_b32_e32 v42, v51
	v_add_f32_e32 v2, v2, v3
	v_mov_b32_e32 v62, v7
	v_mul_f32_e32 v47, v173, v2
	v_pk_mul_f32 v[2:3], v[42:43], v[62:63]
	v_mov_b32_e32 v50, v43
	v_sub_f32_e32 v2, v2, v3
	v_mul_f32_e32 v42, v173, v2
	v_pk_mul_f32 v[2:3], v[50:51], v[62:63]
	v_mov_b32_e32 v6, v4
	v_add_f32_e32 v2, v2, v3
	v_mul_f32_e32 v43, v173, v2
	v_mov_b32_e32 v2, v56
	v_mov_b32_e32 v3, v48
	v_mov_b32_e32 v7, v60
	v_pk_mul_f32 v[2:3], v[2:3], v[6:7]
	v_mov_b32_e32 v60, v5
	v_sub_f32_e32 v2, v2, v3
	v_mul_f32_e32 v4, v173, v2
	v_mov_b32_e32 v2, v48
	v_mov_b32_e32 v3, v56
	v_pk_mul_f32 v[2:3], v[2:3], v[6:7]
	v_mov_b32_e32 v6, v8
; __device__ __forceinline__ void st8(bf16_t* p, const float (&v)[8]) { u32x4 w; w.x = pk2(v[0], v[1]); w.y = pk2(v[2], v[3]); w.z = pk2(v[4], v[5]); w.w = pk2(v[6], v[7]); *(u32x4*)p = w; }
;     __device__ __forceinline__ void operator()(const f32x4 (&acc)[2][2][4][2], const Unit& u, int wr, int wc, int fr, int fq) const {
;     ...
; #pragma unroll
;             for (int ai = 0; ai < 2; ++ai)
; #pragma unroll
;                 for (int m = 0; m < 4; ++m) {
;                     const int row = row0 + ai * 128 + m * 16, pos = row & (SEQ - 1);
;                     const f32x4* cp = (const f32x4*)(cosT + pos * 64 + i0); const f32x4* sp = (const f32x4*)(sinT + pos * 64 + i0);
;                     const f32x4 c0 = cp[0], c1 = cp[1], s0 = sp[0], s1 = sp[1];
;                     float o1[8], o2[8];
; #pragma unroll
;                     for (int j = 0; j < 4; ++j) {
;                         const float a0 = acc[ai][0][m][0][j], b0 = acc[ai][1][m][0][j], a1 = acc[ai][0][m][1][j], b1 = acc[ai][1][m][1][j];
;                         o1[j] = (a0 * c0[j] - b0 * s0[j]) * sc; o2[j] = (b0 * c0[j] + a0 * s0[j]) * sc;
;                         o1[4 + j] = (a1 * c1[j] - b1 * s1[j]) * sc; o2[4 + j] = (b1 * c1[j] + a1 * s1[j]) * sc;
;                     }
;                     bf16_t* rp = dst + (size_t)row * AW + head * 128 + i0;
;                     st8(rp, o1); st8(rp + 64, o2);
	v_add_f32_e32 v2, v2, v3
	v_mul_f32_e32 v50, v173, v2
	v_mov_b32_e32 v2, v52
	v_mov_b32_e32 v3, v44
	v_mov_b32_e32 v7, v64
	v_pk_mul_f32 v[2:3], v[2:3], v[6:7]
	v_mov_b32_e32 v48, v57
	v_sub_f32_e32 v2, v2, v3
	v_mul_f32_e32 v8, v173, v2
	v_mov_b32_e32 v2, v44
	v_mov_b32_e32 v3, v52
	v_pk_mul_f32 v[2:3], v[2:3], v[6:7]
	v_mov_b32_e32 v56, v49
	v_add_f32_e32 v2, v2, v3
	v_mul_f32_e32 v51, v173, v2
	v_pk_mul_f32 v[2:3], v[48:49], v[60:61]
	v_mov_b32_e32 v44, v53
	v_sub_f32_e32 v2, v2, v3
	v_mul_f32_e32 v5, v173, v2
	v_pk_mul_f32 v[2:3], v[56:57], v[60:61]
	v_mov_b32_e32 v64, v9
	v_add_f32_e32 v2, v2, v3
	v_mul_f32_e32 v48, v173, v2
	v_pk_mul_f32 v[2:3], v[44:45], v[64:65]
	v_mov_b32_e32 v52, v45
	v_sub_f32_e32 v2, v2, v3
	v_mul_f32_e32 v9, v173, v2
	v_pk_mul_f32 v[2:3], v[52:53], v[64:65]
	v_mul_f32_e32 v0, v173, v0
	v_add_f32_e32 v2, v2, v3
	v_mul_f32_e32 v44, v173, v2
	v_lshlrev_b64 v[2:3], 11, v[66:67]
	v_lshl_add_u64 v[6:7], v[166:167], 0, v[2:3]
	v_cvt_pk_bf16_f32 v3, v4, v5
	v_cvt_pk_bf16_f32 v2, v0, v46
	v_cvt_pk_bf16_f32 v4, v73, v42
	v_cvt_pk_bf16_f32 v5, v8, v9
	global_store_dwordx4 v[6:7], v[2:5], off
	v_mov_b32_e32 v52, v38
	v_mov_b32_e32 v53, v30
	v_cvt_pk_bf16_f32 v3, v50, v48
	v_add_u32_e32 v50, 0xa0, v164
	v_lshlrev_b32_e32 v0, 8, v50
	v_and_b32_e32 v0, 0xfef00, v0
	v_cvt_pk_bf16_f32 v2, v72, v47
	v_cvt_pk_bf16_f32 v4, v68, v43
	v_cvt_pk_bf16_f32 v5, v51, v44
	global_store_dwordx4 v[6:7], v[2:5], off offset:128
	v_lshl_add_u64 v[6:7], v[154:155], 0, v[0:1]
	v_lshl_add_u64 v[46:47], v[156:157], 0, v[0:1]
	v_ashrrev_i32_e32 v51, 31, v50
	s_waitcnt vmcnt(10) lgkmcnt(0)
	v_mov_b32_e32 v2, v186
	v_mov_b32_e32 v3, v187
	v_mov_b32_e32 v4, v188
	v_mov_b32_e32 v5, v189
	v_mov_b32_e32 v6, v190
	v_mov_b32_e32 v7, v191
	v_mov_b32_e32 v8, v192
	v_mov_b32_e32 v9, v193
	v_mov_b32_e32 v42, v194
	v_mov_b32_e32 v43, v195
	v_mov_b32_e32 v44, v196
	v_mov_b32_e32 v45, v197
	v_mov_b32_e32 v46, v198
	v_mov_b32_e32 v47, v199
	v_mov_b32_e32 v48, v200
	v_mov_b32_e32 v49, v201
	v_mov_b32_e32 v54, v2
	v_mov_b32_e32 v55, v42
	v_pk_mul_f32 v[52:53], v[52:53], v[54:55]
	v_mov_b32_e32 v42, v3
	v_sub_f32_e32 v0, v52, v53
	v_mov_b32_e32 v52, v30
	v_mov_b32_e32 v53, v38
	v_pk_mul_f32 v[52:53], v[52:53], v[54:55]
	v_mov_b32_e32 v54, v6
	v_add_f32_e32 v2, v52, v53
	v_mov_b32_e32 v52, v34
	v_mov_b32_e32 v53, v26
	v_mov_b32_e32 v55, v46
	v_pk_mul_f32 v[52:53], v[52:53], v[54:55]
	v_mul_f32_e32 v56, v173, v2
	v_sub_f32_e32 v2, v52, v53
	v_mov_b32_e32 v52, v26
	v_mov_b32_e32 v53, v34
	v_pk_mul_f32 v[52:53], v[52:53], v[54:55]
	v_mul_f32_e32 v57, v173, v2
	v_add_f32_e32 v2, v52, v53
	v_mov_b32_e32 v30, v39
	v_mul_f32_e32 v52, v173, v2
	v_pk_mul_f32 v[2:3], v[30:31], v[42:43]
	v_mov_b32_e32 v38, v31
	v_sub_f32_e32 v2, v2, v3
	v_mul_f32_e32 v30, v173, v2
	v_pk_mul_f32 v[2:3], v[38:39], v[42:43]
	v_mov_b32_e32 v26, v35
	v_add_f32_e32 v2, v2, v3
	v_mov_b32_e32 v46, v7
	v_mul_f32_e32 v31, v173, v2
	v_pk_mul_f32 v[2:3], v[26:27], v[46:47]
	v_mov_b32_e32 v34, v27
	v_sub_f32_e32 v2, v2, v3
	v_mul_f32_e32 v26, v173, v2
	v_pk_mul_f32 v[2:3], v[34:35], v[46:47]
	v_mov_b32_e32 v6, v4
	v_add_f32_e32 v2, v2, v3
	v_mul_f32_e32 v27, v173, v2
	v_mov_b32_e32 v2, v40
	v_mov_b32_e32 v3, v32
	v_mov_b32_e32 v7, v44
	v_pk_mul_f32 v[2:3], v[2:3], v[6:7]
	v_mov_b32_e32 v44, v5
	v_sub_f32_e32 v2, v2, v3
	v_mul_f32_e32 v4, v173, v2
	v_mov_b32_e32 v2, v32
	v_mov_b32_e32 v3, v40
	v_pk_mul_f32 v[2:3], v[2:3], v[6:7]
	v_mov_b32_e32 v6, v8
	v_add_f32_e32 v2, v2, v3
	v_mul_f32_e32 v34, v173, v2
	v_mov_b32_e32 v2, v36
	v_mov_b32_e32 v3, v28
	v_mov_b32_e32 v7, v48
	v_pk_mul_f32 v[2:3], v[2:3], v[6:7]
	v_mov_b32_e32 v32, v41
	v_sub_f32_e32 v2, v2, v3
	v_mul_f32_e32 v8, v173, v2
	v_mov_b32_e32 v2, v28
	v_mov_b32_e32 v3, v36
	v_pk_mul_f32 v[2:3], v[2:3], v[6:7]
	v_mov_b32_e32 v40, v33
	v_add_f32_e32 v2, v2, v3
	v_mul_f32_e32 v35, v173, v2
	v_pk_mul_f32 v[2:3], v[32:33], v[44:45]
	v_mov_b32_e32 v28, v37
	v_sub_f32_e32 v2, v2, v3
	v_mul_f32_e32 v5, v173, v2
	v_pk_mul_f32 v[2:3], v[40:41], v[44:45]
	v_mov_b32_e32 v48, v9
	v_add_f32_e32 v2, v2, v3
	v_mul_f32_e32 v32, v173, v2
	v_pk_mul_f32 v[2:3], v[28:29], v[48:49]
	v_mov_b32_e32 v36, v29
	v_sub_f32_e32 v2, v2, v3
	v_mul_f32_e32 v9, v173, v2
	v_pk_mul_f32 v[2:3], v[36:37], v[48:49]
	v_mul_f32_e32 v0, v173, v0
	v_add_f32_e32 v2, v2, v3
	v_mul_f32_e32 v28, v173, v2
	v_lshlrev_b64 v[2:3], 11, v[50:51]
	v_lshl_add_u64 v[6:7], v[166:167], 0, v[2:3]
	v_cvt_pk_bf16_f32 v3, v4, v5
	v_cvt_pk_bf16_f32 v2, v0, v30
	v_cvt_pk_bf16_f32 v4, v57, v26
	v_cvt_pk_bf16_f32 v5, v8, v9
	global_store_dwordx4 v[6:7], v[2:5], off
	v_mov_b32_e32 v36, v22
	v_mov_b32_e32 v37, v14
	v_cvt_pk_bf16_f32 v3, v34, v32
	v_add_u32_e32 v34, 0xb0, v164
	v_lshlrev_b32_e32 v0, 8, v34
	v_and_b32_e32 v0, 0xfff00, v0
	v_cvt_pk_bf16_f32 v2, v56, v31
	v_cvt_pk_bf16_f32 v4, v52, v27
	v_cvt_pk_bf16_f32 v5, v35, v28
	global_store_dwordx4 v[6:7], v[2:5], off offset:128
	v_lshl_add_u64 v[6:7], v[154:155], 0, v[0:1]
	v_lshl_add_u64 v[30:31], v[156:157], 0, v[0:1]
	v_ashrrev_i32_e32 v35, 31, v34
	s_waitcnt vmcnt(6) lgkmcnt(0)
; __device__ __forceinline__ void st8(bf16_t* p, const float (&v)[8]) { u32x4 w; w.x = pk2(v[0], v[1]); w.y = pk2(v[2], v[3]); w.z = pk2(v[4], v[5]); w.w = pk2(v[6], v[7]); *(u32x4*)p = w; }
;     __device__ __forceinline__ void operator()(const f32x4 (&acc)[2][2][4][2], const Unit& u, int wr, int wc, int fr, int fq) const {
;     ...
; #pragma unroll
;             for (int ai = 0; ai < 2; ++ai)
; #pragma unroll
;                 for (int m = 0; m < 4; ++m) {
;                     const int row = row0 + ai * 128 + m * 16, pos = row & (SEQ - 1);
;                     const f32x4* cp = (const f32x4*)(cosT + pos * 64 + i0); const f32x4* sp = (const f32x4*)(sinT + pos * 64 + i0);
;                     const f32x4 c0 = cp[0], c1 = cp[1], s0 = sp[0], s1 = sp[1];
;                     float o1[8], o2[8];
; #pragma unroll
;                     for (int j = 0; j < 4; ++j) {
;                         const float a0 = acc[ai][0][m][0][j], b0 = acc[ai][1][m][0][j], a1 = acc[ai][0][m][1][j], b1 = acc[ai][1][m][1][j];
;                         o1[j] = (a0 * c0[j] - b0 * s0[j]) * sc; o2[j] = (b0 * c0[j] + a0 * s0[j]) * sc;
;                         o1[4 + j] = (a1 * c1[j] - b1 * s1[j]) * sc; o2[4 + j] = (b1 * c1[j] + a1 * s1[j]) * sc;
;                     }
;                     bf16_t* rp = dst + (size_t)row * AW + head * 128 + i0;
;                     st8(rp, o1); st8(rp + 64, o2);
	v_mov_b32_e32 v2, v202
	v_mov_b32_e32 v3, v203
	v_mov_b32_e32 v4, v204
	v_mov_b32_e32 v5, v205
	v_mov_b32_e32 v6, v206
	v_mov_b32_e32 v7, v207
	v_mov_b32_e32 v8, v208
	v_mov_b32_e32 v9, v209
	v_mov_b32_e32 v26, v210
	v_mov_b32_e32 v27, v211
	v_mov_b32_e32 v28, v212
	v_mov_b32_e32 v29, v213
	v_mov_b32_e32 v30, v214
	v_mov_b32_e32 v31, v215
	v_mov_b32_e32 v32, v216
	v_mov_b32_e32 v33, v217
	v_mov_b32_e32 v38, v2
	v_mov_b32_e32 v39, v26
	v_pk_mul_f32 v[36:37], v[36:37], v[38:39]
	v_mov_b32_e32 v26, v3
	v_sub_f32_e32 v0, v36, v37
	v_mov_b32_e32 v36, v14
	v_mov_b32_e32 v37, v22
	v_pk_mul_f32 v[36:37], v[36:37], v[38:39]
	v_mov_b32_e32 v38, v6
	v_add_f32_e32 v2, v36, v37
	v_mov_b32_e32 v36, v18
	v_mov_b32_e32 v37, v10
	v_mov_b32_e32 v39, v30
	v_pk_mul_f32 v[36:37], v[36:37], v[38:39]
	v_mul_f32_e32 v40, v173, v2
	v_sub_f32_e32 v2, v36, v37
	v_mov_b32_e32 v36, v10
	v_mov_b32_e32 v37, v18
	v_pk_mul_f32 v[36:37], v[36:37], v[38:39]
	v_mul_f32_e32 v41, v173, v2
	v_add_f32_e32 v2, v36, v37
	v_mov_b32_e32 v14, v23
	v_mul_f32_e32 v36, v173, v2
	v_pk_mul_f32 v[2:3], v[14:15], v[26:27]
	v_mov_b32_e32 v22, v15
	v_sub_f32_e32 v2, v2, v3
	v_mul_f32_e32 v14, v173, v2
	v_pk_mul_f32 v[2:3], v[22:23], v[26:27]
	v_mov_b32_e32 v10, v19
	v_add_f32_e32 v2, v2, v3
	v_mov_b32_e32 v30, v7
	v_mul_f32_e32 v15, v173, v2
	v_pk_mul_f32 v[2:3], v[10:11], v[30:31]
	v_mov_b32_e32 v18, v11
	v_sub_f32_e32 v2, v2, v3
	v_mul_f32_e32 v10, v173, v2
	v_pk_mul_f32 v[2:3], v[18:19], v[30:31]
	v_mov_b32_e32 v6, v4
	v_add_f32_e32 v2, v2, v3
	v_mul_f32_e32 v11, v173, v2
	v_mov_b32_e32 v2, v24
	v_mov_b32_e32 v3, v16
	v_mov_b32_e32 v7, v28
	v_pk_mul_f32 v[2:3], v[2:3], v[6:7]
	v_mov_b32_e32 v28, v5
	v_sub_f32_e32 v2, v2, v3
	v_mul_f32_e32 v4, v173, v2
	v_mov_b32_e32 v2, v16
	v_mov_b32_e32 v3, v24
	v_pk_mul_f32 v[2:3], v[2:3], v[6:7]
	v_mov_b32_e32 v6, v8
	v_add_f32_e32 v2, v2, v3
	v_mul_f32_e32 v18, v173, v2
	v_mov_b32_e32 v2, v20
	v_mov_b32_e32 v3, v12
	v_mov_b32_e32 v7, v32
	v_pk_mul_f32 v[2:3], v[2:3], v[6:7]
	v_mov_b32_e32 v16, v25
	v_sub_f32_e32 v2, v2, v3
	v_mul_f32_e32 v8, v173, v2
	v_mov_b32_e32 v2, v12
	v_mov_b32_e32 v3, v20
	v_pk_mul_f32 v[2:3], v[2:3], v[6:7]
	v_mov_b32_e32 v24, v17
	v_add_f32_e32 v2, v2, v3
	v_mul_f32_e32 v19, v173, v2
	v_pk_mul_f32 v[2:3], v[16:17], v[28:29]
	v_mov_b32_e32 v12, v21
	v_sub_f32_e32 v2, v2, v3
	v_mul_f32_e32 v5, v173, v2
	v_pk_mul_f32 v[2:3], v[24:25], v[28:29]
	v_mov_b32_e32 v32, v9
	v_add_f32_e32 v2, v2, v3
	v_mul_f32_e32 v16, v173, v2
	v_pk_mul_f32 v[2:3], v[12:13], v[32:33]
	v_mov_b32_e32 v20, v13
	v_sub_f32_e32 v2, v2, v3
	v_mul_f32_e32 v9, v173, v2
	v_pk_mul_f32 v[2:3], v[20:21], v[32:33]
	v_mul_f32_e32 v0, v173, v0
	v_add_f32_e32 v2, v2, v3
	v_mul_f32_e32 v12, v173, v2
	v_lshlrev_b64 v[2:3], 11, v[34:35]
	v_lshl_add_u64 v[6:7], v[166:167], 0, v[2:3]
	v_cvt_pk_bf16_f32 v2, v0, v14
	v_cvt_pk_bf16_f32 v3, v4, v5
	v_cvt_pk_bf16_f32 v4, v41, v10
	v_cvt_pk_bf16_f32 v5, v8, v9
	global_store_dwordx4 v[6:7], v[2:5], off
	s_nop 1
	v_cvt_pk_bf16_f32 v2, v40, v15
	v_cvt_pk_bf16_f32 v3, v18, v16
	v_cvt_pk_bf16_f32 v4, v36, v11
	v_cvt_pk_bf16_f32 v5, v19, v12
	global_store_dwordx4 v[6:7], v[2:5], off offset:128
	s_andn2_b64 vcc, exec, s[40:41]
	s_mov_b64 s[12:13], -1
	s_cbranch_vccnz .LBB0_343
	s_branch .LBB0_747
